# grid barrier: non-leader workgroups issue their L1 invalidate (buffer_inv sc1) before spinning on the release word instead of after it; only sc1 polling loads run in between
# speedup vs baseline: 1.0122x; 1.0046x over previous
; __device__ __forceinline__ unsigned xb_ld(unsigned* p)              { return __hip_atomic_load(p, __ATOMIC_RELAXED, __HIP_MEMORY_SCOPE_AGENT); }
; __device__ __forceinline__ unsigned xb_add(unsigned* p, unsigned v) { return __hip_atomic_fetch_add(p, v, __ATOMIC_RELAXED, __HIP_MEMORY_SCOPE_AGENT); }
; #define XB_SPIN(cond, bar) do { unsigned _sp = 0; while (cond) { __builtin_amdgcn_s_sleep(1); \
;     if ((++_sp & 255u) == 0u) { if (xb_ld(&(bar)[XB_TMO])) break; if (_sp > XB_SPIN_CAP) { atomicAdd(&(bar)[XB_TMO], 1u); break; } } } } while (0)
; __device__ __forceinline__ void xcd_barrier(const XcdBarrier& b, const bool t0) {
;     ...
;         const unsigned old = xb_add(&bar[XB_XSUB(b.x)], 1u);
;         const unsigned gen = old / nloc;
;         if (old + 1u == (gen + 1u) * nloc) {
;             __builtin_amdgcn_fence(__ATOMIC_RELEASE, "agent");
;             asm volatile("s_waitcnt vmcnt(0)" ::: "memory");
;             const unsigned og = xb_add(&bar[XB_TOP], 1u);
;             const unsigned tg = og / nx;
;             if (og + 1u == (tg + 1u) * nx) xb_add(&bar[XB_TOPGEN], 1u);
;             else XB_SPIN(xb_ld(&bar[XB_TOPGEN]) == tg, bar);
;             __builtin_amdgcn_fence(__ATOMIC_ACQUIRE, "agent");
;             xb_add(&bar[XB_XGEN(b.x)], 1u);
;             asm volatile("s_waitcnt vmcnt(0)" ::: "memory");
;         } else {
;             XB_SPIN(xb_ld(&bar[XB_XGEN(b.x)]) == gen, bar);
;             __builtin_amdgcn_fence(__ATOMIC_ACQUIRE, "agent");
.LBB0_391:
	s_or_b64 exec, exec, s[4:5]
	v_cvt_f32_u32_e32 v5, v3
	s_waitcnt vmcnt(0)
	v_readfirstlane_b32 s4, v4
	v_sub_u32_e32 v4, 0, v3
	v_rcp_iflag_f32_e32 v5, v5
	v_add_u32_e32 v6, s4, v0
	v_mul_f32_e32 v5, 0x4f7ffffe, v5
	v_cvt_u32_f32_e32 v5, v5
	v_mul_lo_u32 v0, v4, v5
	v_mul_hi_u32 v0, v5, v0
	v_add_u32_e32 v0, v5, v0
	v_mul_hi_u32 v0, v6, v0
	v_mul_lo_u32 v4, v0, v3
	v_sub_u32_e32 v4, v6, v4
	v_add_u32_e32 v5, 1, v0
	v_cmp_ge_u32_e32 vcc, v4, v3
	s_nop 1
	v_cndmask_b32_e32 v0, v0, v5, vcc
	v_sub_u32_e32 v5, v4, v3
	v_cndmask_b32_e32 v4, v4, v5, vcc
	v_add_u32_e32 v5, 1, v0
	v_cmp_ge_u32_e32 vcc, v4, v3
	v_add_u32_e32 v4, 1, v6
	s_nop 0
	v_cndmask_b32_e32 v0, v0, v5, vcc
	v_mul_lo_u32 v5, v3, v0
	v_add_u32_e32 v3, v5, v3
	v_cmp_ne_u32_e32 vcc, v4, v3
	s_and_saveexec_b64 s[4:5], vcc
	s_xor_b64 s[4:5], exec, s[4:5]
	s_cbranch_execz .LBB0_405
	buffer_inv sc1
	v_readlane_b32 s6, v253, 23
	v_readlane_b32 s7, v253, 24
	s_waitcnt lgkmcnt(0)
	s_nop 3
	global_load_dword v2, v1, s[6:7] sc1
	s_waitcnt vmcnt(0)
	v_cmp_eq_u32_e32 vcc, v2, v0
	s_and_saveexec_b64 s[6:7], vcc
	s_cbranch_execz .LBB0_404
	s_mov_b32 s12, 1
	s_mov_b64 s[8:9], 0
	s_branch .LBB0_395

; __device__ __forceinline__ unsigned xb_ld(unsigned* p)              { return __hip_atomic_load(p, __ATOMIC_RELAXED, __HIP_MEMORY_SCOPE_AGENT); }
; #define XB_SPIN(cond, bar) do { unsigned _sp = 0; while (cond) { __builtin_amdgcn_s_sleep(1); \
;     if ((++_sp & 255u) == 0u) { if (xb_ld(&(bar)[XB_TMO])) break; if (_sp > XB_SPIN_CAP) { atomicAdd(&(bar)[XB_TMO], 1u); break; } } } } while (0)
; __device__ __forceinline__ void xcd_barrier(const XcdBarrier& b, const bool t0) {
;     ...
;             XB_SPIN(xb_ld(&bar[XB_XGEN(b.x)]) == gen, bar);
;             __builtin_amdgcn_fence(__ATOMIC_ACQUIRE, "agent");
;             asm volatile("s_waitcnt vmcnt(0)" ::: "memory");
.LBB0_404:
	s_or_b64 exec, exec, s[6:7]
	s_waitcnt vmcnt(0)
	s_waitcnt vmcnt(0)
